# v16: barrier acquire (buffer_inv) issued at arrival right behind the arrive atomic so its latency overlaps the wait; assumption: no data loads are issued by the workgroup between arrival and completio
# speedup vs baseline: 1.0134x; 1.0134x over previous
; DI unsigned xb_ld(unsigned* p)              { return __hip_atomic_load(p, __ATOMIC_RELAXED, __HIP_MEMORY_SCOPE_AGENT); }
; DI unsigned xb_add(unsigned* p, unsigned v) { return __hip_atomic_fetch_add(p, v, __ATOMIC_RELAXED, __HIP_MEMORY_SCOPE_AGENT); }
; #define XB_SPIN(cond, bar) do { unsigned _sp = 0; while (cond) { \
;     if ((++_sp & 255u) == 0u) { if (xb_ld(&(bar)[XB_TMO])) break; if (_sp > XB_SPIN_CAP) { atomicAdd(&(bar)[XB_TMO], 1u); break; } } } } while (0)
; #define GSYNC() do { XcdBarrier _b; _b.bar = (unsigned*)(get_ka()->ws); _b.x = xb_xcc_id(); _b.st = (volatile LAS unsigned*)(lds + 147200); xcd_barrier(_b); } while (0)
; DI void xcd_barrier(const XcdBarrier& b) {
;     asm volatile("s_waitcnt vmcnt(0)" ::: "memory");
;     __syncthreads();
;     if (threadIdx.x == 0) {
;         unsigned* bar = b.bar;
;         __builtin_amdgcn_s_waitcnt(0);
;         unsigned nloc = b.st[0], nx = b.st[1];
;         if (nloc == 0u) { xcd_barrier_complete(bar, b.x, nloc, nx); b.st[0] = nloc; b.st[1] = nx; }
;         const unsigned old = xb_add(&bar[XB_XSUB(b.x)], 1u);
;         const unsigned gen = old / nloc;
;         if (old + 1u == (gen + 1u) * nloc) {
;             __builtin_amdgcn_fence(__ATOMIC_RELEASE, "agent");
;             asm volatile("s_waitcnt vmcnt(0)" ::: "memory");
;             const unsigned og = xb_add(&bar[XB_TOP], 1u);
;             const unsigned tg = og / nx;
;             if (og + 1u == (tg + 1u) * nx) xb_add(&bar[XB_TOPGEN], 1u);
;             else XB_SPIN(xb_ld(&bar[XB_TOPGEN]) == tg, bar);
;             __builtin_amdgcn_fence(__ATOMIC_ACQUIRE, "agent");
;             xb_add(&bar[XB_XGEN(b.x)], 1u);
;             asm volatile("s_waitcnt vmcnt(0)" ::: "memory");
;         } else {
;             XB_SPIN(xb_ld(&bar[XB_XGEN(b.x)]) == gen, bar);
;             __builtin_amdgcn_fence(__ATOMIC_ACQUIRE, "agent");
;             asm volatile("s_waitcnt vmcnt(0)" ::: "memory");
;         }
;     }
;     __syncthreads();
; }
; __global__ void __launch_bounds__(512, 2) hymba_fwd(Args a_unused) {
;     ...
;     GSYNC();
.LBB0_227:
	s_or_b64 exec, exec, s[12:13]
	v_readlane_b32 s4, v254, 4
	v_readlane_b32 s5, v254, 5
	s_barrier
	s_getreg_b32 s0, hwreg(HW_REG_XCC_ID, 0, 4)
	s_waitcnt vmcnt(0)
	s_barrier
	s_mov_b64 s[2:3], exec
	v_readlane_b32 s6, v254, 1
	v_readlane_b32 s7, v254, 2
	s_and_b64 s[6:7], s[2:3], s[6:7]
	s_xor_b64 s[2:3], s[6:7], s[2:3]
	s_mov_b64 exec, s[6:7]
	s_cbranch_execz .LBB0_280
	s_load_dwordx2 s[4:5], s[4:5], 0xd8
	v_mov_b32_e32 v0, 0x23f00
	ds_read_b32 v2, v0
	s_and_b32 s0, s0, 15
	s_lshl_b32 s12, s0, 8
	s_lshl_b32 s14, s0, 2
	v_mov_b32_e32 v3, 1
	v_mov_b32_e32 v1, 0x1000
	s_waitcnt lgkmcnt(0)
	s_add_u32 s6, s4, s12
	s_addc_u32 s7, s5, 0
	global_atomic_add v3, v1, v3, s[6:7] offset:1024 sc0
	buffer_inv sc1
	v_cvt_f32_u32_e32 v4, v2
	v_sub_u32_e32 v0, 0, v2
	v_rcp_iflag_f32_e32 v4, v4
	s_waitcnt vmcnt(1)
	v_mov_b32_e32 v5, v3
	v_mul_f32_e32 v4, 0x4f7ffffe, v4
	v_cvt_u32_f32_e32 v4, v4
	v_mul_lo_u32 v1, v0, v4
	v_mul_hi_u32 v1, v4, v1
	v_add_u32_e32 v1, v4, v1
	v_mul_hi_u32 v1, v5, v1
	v_mul_lo_u32 v3, v1, v2
	v_sub_u32_e32 v3, v5, v3
	v_add_u32_e32 v4, 1, v1
	v_cmp_ge_u32_e32 vcc, v3, v2
	s_nop 1
	v_cndmask_b32_e32 v1, v1, v4, vcc
	v_sub_u32_e32 v4, v3, v2
	v_cndmask_b32_e32 v3, v3, v4, vcc
	v_add_u32_e32 v4, 1, v1
	v_cmp_ge_u32_e32 vcc, v3, v2
	s_nop 1
	v_cndmask_b32_e32 v1, v1, v4, vcc
	v_mul_lo_u32 v4, v2, v1
	v_add_u32_e32 v4, v4, v2
	v_add_u32_e32 v3, 1, v5
	v_readfirstlane_b32 s10, v1
	v_cmp_ne_u32_e32 vcc, v3, v4
	s_cbranch_vccnz .Lgb0_poll
	buffer_wbl2 sc1
	s_add_i32 s11, s10, 1
	v_mov_b32_e32 v0, s14
	v_mov_b32_e32 v1, s11
	v_add_u32_e32 v0, 0x3800, v0
	s_waitcnt vmcnt(0)
	global_store_dword v0, v1, s[4:5] sc1

; DI unsigned xb_ld(unsigned* p)              { return __hip_atomic_load(p, __ATOMIC_RELAXED, __HIP_MEMORY_SCOPE_AGENT); }
; #define XB_SPIN(cond, bar) do { unsigned _sp = 0; while (cond) { \
;     if ((++_sp & 255u) == 0u) { if (xb_ld(&(bar)[XB_TMO])) break; if (_sp > XB_SPIN_CAP) { atomicAdd(&(bar)[XB_TMO], 1u); break; } } } } while (0)
; DI void xcd_barrier(const XcdBarrier& b) {
;     ...
;             XB_SPIN(xb_ld(&bar[XB_XGEN(b.x)]) == gen, bar);
;             __builtin_amdgcn_fence(__ATOMIC_ACQUIRE, "agent");
;             asm volatile("s_waitcnt vmcnt(0)" ::: "memory");
;         }
.Lgb0_done:
	s_waitcnt vmcnt(0)
	s_branch .LBB0_280

; DI unsigned xb_ld(unsigned* p)              { return __hip_atomic_load(p, __ATOMIC_RELAXED, __HIP_MEMORY_SCOPE_AGENT); }
; DI unsigned xb_add(unsigned* p, unsigned v) { return __hip_atomic_fetch_add(p, v, __ATOMIC_RELAXED, __HIP_MEMORY_SCOPE_AGENT); }
; #define XB_SPIN(cond, bar) do { unsigned _sp = 0; while (cond) { \
;     if ((++_sp & 255u) == 0u) { if (xb_ld(&(bar)[XB_TMO])) break; if (_sp > XB_SPIN_CAP) { atomicAdd(&(bar)[XB_TMO], 1u); break; } } } } while (0)
; DI void xcd_barrier(const XcdBarrier& b) {
;     asm volatile("s_waitcnt vmcnt(0)" ::: "memory");
;     __syncthreads();
;     if (threadIdx.x == 0) {
;         unsigned* bar = b.bar;
;         __builtin_amdgcn_s_waitcnt(0);
;         unsigned nloc = b.st[0], nx = b.st[1];
;         if (nloc == 0u) { xcd_barrier_complete(bar, b.x, nloc, nx); b.st[0] = nloc; b.st[1] = nx; }
;         const unsigned old = xb_add(&bar[XB_XSUB(b.x)], 1u);
;         const unsigned gen = old / nloc;
;         if (old + 1u == (gen + 1u) * nloc) {
;             __builtin_amdgcn_fence(__ATOMIC_RELEASE, "agent");
;             asm volatile("s_waitcnt vmcnt(0)" ::: "memory");
;             const unsigned og = xb_add(&bar[XB_TOP], 1u);
;             const unsigned tg = og / nx;
;             if (og + 1u == (tg + 1u) * nx) xb_add(&bar[XB_TOPGEN], 1u);
;             else XB_SPIN(xb_ld(&bar[XB_TOPGEN]) == tg, bar);
;             __builtin_amdgcn_fence(__ATOMIC_ACQUIRE, "agent");
;             xb_add(&bar[XB_XGEN(b.x)], 1u);
;             asm volatile("s_waitcnt vmcnt(0)" ::: "memory");
;         } else {
;             XB_SPIN(xb_ld(&bar[XB_XGEN(b.x)]) == gen, bar);
;             __builtin_amdgcn_fence(__ATOMIC_ACQUIRE, "agent");
;             asm volatile("s_waitcnt vmcnt(0)" ::: "memory");
;         }
;     }
;     __syncthreads();
; }
.LBB0_301:
	v_readlane_b32 s4, v254, 4
	v_readlane_b32 s5, v254, 5
	s_getreg_b32 s0, hwreg(HW_REG_XCC_ID, 0, 4)
	s_waitcnt vmcnt(0)
	s_barrier
	s_mov_b64 s[2:3], exec
	v_readlane_b32 s6, v254, 1
	v_readlane_b32 s7, v254, 2
	s_and_b64 s[6:7], s[2:3], s[6:7]
	s_mov_b64 exec, s[6:7]
	s_cbranch_execz .LBB0_353
	s_load_dwordx2 s[4:5], s[4:5], 0xd8
	v_mov_b32_e32 v0, 0x23f00
	ds_read_b32 v2, v0
	s_and_b32 s0, s0, 15
	s_lshl_b32 s12, s0, 8
	s_lshl_b32 s14, s0, 2
	v_mov_b32_e32 v3, 1
	v_mov_b32_e32 v1, 0x1000
	s_waitcnt lgkmcnt(0)
	s_add_u32 s6, s4, s12
	s_addc_u32 s7, s5, 0
	global_atomic_add v3, v1, v3, s[6:7] offset:1024 sc0
	buffer_inv sc1
	v_cvt_f32_u32_e32 v4, v2
	v_sub_u32_e32 v0, 0, v2
	v_rcp_iflag_f32_e32 v4, v4
	s_waitcnt vmcnt(1)
	v_mov_b32_e32 v5, v3
	v_mul_f32_e32 v4, 0x4f7ffffe, v4
	v_cvt_u32_f32_e32 v4, v4
	v_mul_lo_u32 v1, v0, v4
	v_mul_hi_u32 v1, v4, v1
	v_add_u32_e32 v1, v4, v1
	v_mul_hi_u32 v1, v5, v1
	v_mul_lo_u32 v3, v1, v2
	v_sub_u32_e32 v3, v5, v3
	v_add_u32_e32 v4, 1, v1
	v_cmp_ge_u32_e32 vcc, v3, v2
	s_nop 1
	v_cndmask_b32_e32 v1, v1, v4, vcc
	v_sub_u32_e32 v4, v3, v2
	v_cndmask_b32_e32 v3, v3, v4, vcc
	v_add_u32_e32 v4, 1, v1
	v_cmp_ge_u32_e32 vcc, v3, v2
	s_nop 1
	v_cndmask_b32_e32 v1, v1, v4, vcc
	v_mul_lo_u32 v4, v2, v1
	v_add_u32_e32 v4, v4, v2
	v_add_u32_e32 v3, 1, v5
	v_readfirstlane_b32 s10, v1
	v_cmp_ne_u32_e32 vcc, v3, v4
	s_cbranch_vccnz .Lgb1_poll
	buffer_wbl2 sc1
	s_add_i32 s11, s10, 1
	v_mov_b32_e32 v0, s14
	v_mov_b32_e32 v1, s11
	v_add_u32_e32 v0, 0x3800, v0
	s_waitcnt vmcnt(0)
	global_store_dword v0, v1, s[4:5] sc1

; DI unsigned xb_ld(unsigned* p)              { return __hip_atomic_load(p, __ATOMIC_RELAXED, __HIP_MEMORY_SCOPE_AGENT); }
; DI unsigned xb_add(unsigned* p, unsigned v) { return __hip_atomic_fetch_add(p, v, __ATOMIC_RELAXED, __HIP_MEMORY_SCOPE_AGENT); }
; #define XB_SPIN(cond, bar) do { unsigned _sp = 0; while (cond) { \
;     if ((++_sp & 255u) == 0u) { if (xb_ld(&(bar)[XB_TMO])) break; if (_sp > XB_SPIN_CAP) { atomicAdd(&(bar)[XB_TMO], 1u); break; } } } } while (0)
; DI void xcd_barrier(const XcdBarrier& b) {
;     asm volatile("s_waitcnt vmcnt(0)" ::: "memory");
;     __syncthreads();
;     if (threadIdx.x == 0) {
;         unsigned* bar = b.bar;
;         __builtin_amdgcn_s_waitcnt(0);
;         unsigned nloc = b.st[0], nx = b.st[1];
;         if (nloc == 0u) { xcd_barrier_complete(bar, b.x, nloc, nx); b.st[0] = nloc; b.st[1] = nx; }
;         const unsigned old = xb_add(&bar[XB_XSUB(b.x)], 1u);
;         const unsigned gen = old / nloc;
;         if (old + 1u == (gen + 1u) * nloc) {
;             __builtin_amdgcn_fence(__ATOMIC_RELEASE, "agent");
;             asm volatile("s_waitcnt vmcnt(0)" ::: "memory");
;             const unsigned og = xb_add(&bar[XB_TOP], 1u);
;             const unsigned tg = og / nx;
;             if (og + 1u == (tg + 1u) * nx) xb_add(&bar[XB_TOPGEN], 1u);
;             else XB_SPIN(xb_ld(&bar[XB_TOPGEN]) == tg, bar);
;             __builtin_amdgcn_fence(__ATOMIC_ACQUIRE, "agent");
;             xb_add(&bar[XB_XGEN(b.x)], 1u);
;             asm volatile("s_waitcnt vmcnt(0)" ::: "memory");
;         } else {
;             XB_SPIN(xb_ld(&bar[XB_XGEN(b.x)]) == gen, bar);
;             __builtin_amdgcn_fence(__ATOMIC_ACQUIRE, "agent");
;             asm volatile("s_waitcnt vmcnt(0)" ::: "memory");
;         }
;     }
;     __syncthreads();
; }
.LBB0_476:
	v_readlane_b32 s4, v254, 4
	v_readlane_b32 s5, v254, 5
	s_getreg_b32 s0, hwreg(HW_REG_XCC_ID, 0, 4)
	s_waitcnt vmcnt(0)
	s_waitcnt vmcnt(0) lgkmcnt(0)
	s_barrier
	s_mov_b64 s[2:3], exec
	v_readlane_b32 s6, v254, 1
	v_readlane_b32 s7, v254, 2
	s_and_b64 s[6:7], s[2:3], s[6:7]
	s_mov_b64 exec, s[6:7]
	s_cbranch_execz .LBB0_530
	s_load_dwordx2 s[4:5], s[4:5], 0xd8
	v_mov_b32_e32 v0, 0x23f00
	ds_read_b32 v2, v0
	s_and_b32 s0, s0, 15
	s_lshl_b32 s12, s0, 8
	s_lshl_b32 s14, s0, 2
	v_mov_b32_e32 v3, 1
	v_mov_b32_e32 v1, 0x1000
	s_waitcnt lgkmcnt(0)
	s_add_u32 s6, s4, s12
	s_addc_u32 s7, s5, 0
	global_atomic_add v3, v1, v3, s[6:7] offset:1024 sc0
	buffer_inv sc1
	v_cvt_f32_u32_e32 v4, v2
	v_sub_u32_e32 v0, 0, v2
	v_rcp_iflag_f32_e32 v4, v4
	s_waitcnt vmcnt(1)
	v_mov_b32_e32 v5, v3
	v_mul_f32_e32 v4, 0x4f7ffffe, v4
	v_cvt_u32_f32_e32 v4, v4
	v_mul_lo_u32 v1, v0, v4
	v_mul_hi_u32 v1, v4, v1
	v_add_u32_e32 v1, v4, v1
	v_mul_hi_u32 v1, v5, v1
	v_mul_lo_u32 v3, v1, v2
	v_sub_u32_e32 v3, v5, v3
	v_add_u32_e32 v4, 1, v1
	v_cmp_ge_u32_e32 vcc, v3, v2
	s_nop 1
	v_cndmask_b32_e32 v1, v1, v4, vcc
	v_sub_u32_e32 v4, v3, v2
	v_cndmask_b32_e32 v3, v3, v4, vcc
	v_add_u32_e32 v4, 1, v1
	v_cmp_ge_u32_e32 vcc, v3, v2
	s_nop 1
	v_cndmask_b32_e32 v1, v1, v4, vcc
	v_mul_lo_u32 v4, v2, v1
	v_add_u32_e32 v4, v4, v2
	v_add_u32_e32 v3, 1, v5
	v_readfirstlane_b32 s10, v1
	v_cmp_ne_u32_e32 vcc, v3, v4
	s_cbranch_vccnz .Lgb2_poll
	buffer_wbl2 sc1
	s_add_i32 s11, s10, 1
	v_mov_b32_e32 v0, s14
	v_mov_b32_e32 v1, s11
	v_add_u32_e32 v0, 0x3800, v0
	s_waitcnt vmcnt(0)
	global_store_dword v0, v1, s[4:5] sc1

; DI unsigned xb_ld(unsigned* p)              { return __hip_atomic_load(p, __ATOMIC_RELAXED, __HIP_MEMORY_SCOPE_AGENT); }
; DI unsigned xb_add(unsigned* p, unsigned v) { return __hip_atomic_fetch_add(p, v, __ATOMIC_RELAXED, __HIP_MEMORY_SCOPE_AGENT); }
; #define XB_SPIN(cond, bar) do { unsigned _sp = 0; while (cond) { \
;     if ((++_sp & 255u) == 0u) { if (xb_ld(&(bar)[XB_TMO])) break; if (_sp > XB_SPIN_CAP) { atomicAdd(&(bar)[XB_TMO], 1u); break; } } } } while (0)
; DI void xcd_barrier(const XcdBarrier& b) {
;     asm volatile("s_waitcnt vmcnt(0)" ::: "memory");
;     __syncthreads();
;     if (threadIdx.x == 0) {
;         unsigned* bar = b.bar;
;         __builtin_amdgcn_s_waitcnt(0);
;         unsigned nloc = b.st[0], nx = b.st[1];
;         if (nloc == 0u) { xcd_barrier_complete(bar, b.x, nloc, nx); b.st[0] = nloc; b.st[1] = nx; }
;         const unsigned old = xb_add(&bar[XB_XSUB(b.x)], 1u);
;         const unsigned gen = old / nloc;
;         if (old + 1u == (gen + 1u) * nloc) {
;             __builtin_amdgcn_fence(__ATOMIC_RELEASE, "agent");
;             asm volatile("s_waitcnt vmcnt(0)" ::: "memory");
;             const unsigned og = xb_add(&bar[XB_TOP], 1u);
;             const unsigned tg = og / nx;
;             if (og + 1u == (tg + 1u) * nx) xb_add(&bar[XB_TOPGEN], 1u);
;             else XB_SPIN(xb_ld(&bar[XB_TOPGEN]) == tg, bar);
;             __builtin_amdgcn_fence(__ATOMIC_ACQUIRE, "agent");
;             xb_add(&bar[XB_XGEN(b.x)], 1u);
;             asm volatile("s_waitcnt vmcnt(0)" ::: "memory");
;         } else {
;             XB_SPIN(xb_ld(&bar[XB_XGEN(b.x)]) == gen, bar);
;             __builtin_amdgcn_fence(__ATOMIC_ACQUIRE, "agent");
;             asm volatile("s_waitcnt vmcnt(0)" ::: "memory");
;         }
;     }
;     __syncthreads();
; }
.LBB0_599:
	v_readlane_b32 s4, v254, 4
	v_readlane_b32 s5, v254, 5
	s_getreg_b32 s0, hwreg(HW_REG_XCC_ID, 0, 4)
	s_waitcnt vmcnt(0)
	s_waitcnt vmcnt(63) expcnt(7) lgkmcnt(15)
	s_barrier
	s_mov_b64 s[2:3], exec
	v_readlane_b32 s6, v254, 1
	v_readlane_b32 s7, v254, 2
	s_and_b64 s[6:7], s[2:3], s[6:7]
	s_mov_b64 exec, s[6:7]
	s_cbranch_execz .LBB0_728
	s_load_dwordx2 s[4:5], s[4:5], 0xd8
	v_mov_b32_e32 v0, 0x23f00
	ds_read_b32 v2, v0
	s_and_b32 s0, s0, 15
	s_lshl_b32 s12, s0, 8
	s_lshl_b32 s14, s0, 2
	v_mov_b32_e32 v3, 1
	v_mov_b32_e32 v1, 0x1000
	s_waitcnt lgkmcnt(0)
	s_add_u32 s6, s4, s12
	s_addc_u32 s7, s5, 0
	global_atomic_add v3, v1, v3, s[6:7] offset:1024 sc0
	buffer_inv sc1
	v_cvt_f32_u32_e32 v4, v2
	v_sub_u32_e32 v0, 0, v2
	v_rcp_iflag_f32_e32 v4, v4
	s_waitcnt vmcnt(1)
	v_mov_b32_e32 v5, v3
	v_mul_f32_e32 v4, 0x4f7ffffe, v4
	v_cvt_u32_f32_e32 v4, v4
	v_mul_lo_u32 v1, v0, v4
	v_mul_hi_u32 v1, v4, v1
	v_add_u32_e32 v1, v4, v1
	v_mul_hi_u32 v1, v5, v1
	v_mul_lo_u32 v3, v1, v2
	v_sub_u32_e32 v3, v5, v3
	v_add_u32_e32 v4, 1, v1
	v_cmp_ge_u32_e32 vcc, v3, v2
	s_nop 1
	v_cndmask_b32_e32 v1, v1, v4, vcc
	v_sub_u32_e32 v4, v3, v2
	v_cndmask_b32_e32 v3, v3, v4, vcc
	v_add_u32_e32 v4, 1, v1
	v_cmp_ge_u32_e32 vcc, v3, v2
	s_nop 1
	v_cndmask_b32_e32 v1, v1, v4, vcc
	v_mul_lo_u32 v4, v2, v1
	v_add_u32_e32 v4, v4, v2
	v_add_u32_e32 v3, 1, v5
	v_readfirstlane_b32 s10, v1
	v_cmp_ne_u32_e32 vcc, v3, v4
	s_cbranch_vccnz .Lgb4_poll
	buffer_wbl2 sc1
	s_add_i32 s11, s10, 1
	v_mov_b32_e32 v0, s14
	v_mov_b32_e32 v1, s11
	v_add_u32_e32 v0, 0x3800, v0
	s_waitcnt vmcnt(0)
	global_store_dword v0, v1, s[4:5] sc1

; DI unsigned xb_ld(unsigned* p)              { return __hip_atomic_load(p, __ATOMIC_RELAXED, __HIP_MEMORY_SCOPE_AGENT); }
; DI unsigned xb_add(unsigned* p, unsigned v) { return __hip_atomic_fetch_add(p, v, __ATOMIC_RELAXED, __HIP_MEMORY_SCOPE_AGENT); }
; #define XB_SPIN(cond, bar) do { unsigned _sp = 0; while (cond) { \
;     if ((++_sp & 255u) == 0u) { if (xb_ld(&(bar)[XB_TMO])) break; if (_sp > XB_SPIN_CAP) { atomicAdd(&(bar)[XB_TMO], 1u); break; } } } } while (0)
; DI void xcd_barrier(const XcdBarrier& b) {
;     asm volatile("s_waitcnt vmcnt(0)" ::: "memory");
;     __syncthreads();
;     if (threadIdx.x == 0) {
;         unsigned* bar = b.bar;
;         __builtin_amdgcn_s_waitcnt(0);
;         unsigned nloc = b.st[0], nx = b.st[1];
;         if (nloc == 0u) { xcd_barrier_complete(bar, b.x, nloc, nx); b.st[0] = nloc; b.st[1] = nx; }
;         const unsigned old = xb_add(&bar[XB_XSUB(b.x)], 1u);
;         const unsigned gen = old / nloc;
;         if (old + 1u == (gen + 1u) * nloc) {
;             __builtin_amdgcn_fence(__ATOMIC_RELEASE, "agent");
;             asm volatile("s_waitcnt vmcnt(0)" ::: "memory");
;             const unsigned og = xb_add(&bar[XB_TOP], 1u);
;             const unsigned tg = og / nx;
;             if (og + 1u == (tg + 1u) * nx) xb_add(&bar[XB_TOPGEN], 1u);
;             else XB_SPIN(xb_ld(&bar[XB_TOPGEN]) == tg, bar);
;             __builtin_amdgcn_fence(__ATOMIC_ACQUIRE, "agent");
;             xb_add(&bar[XB_XGEN(b.x)], 1u);
;             asm volatile("s_waitcnt vmcnt(0)" ::: "memory");
;         } else {
;             XB_SPIN(xb_ld(&bar[XB_XGEN(b.x)]) == gen, bar);
;             __builtin_amdgcn_fence(__ATOMIC_ACQUIRE, "agent");
;             asm volatile("s_waitcnt vmcnt(0)" ::: "memory");
;         }
;     }
;     __syncthreads();
; }
.LBB0_736:
	s_or_b64 exec, exec, s[2:3]
	v_readlane_b32 s4, v254, 4
	v_readlane_b32 s5, v254, 5
	s_getreg_b32 s0, hwreg(HW_REG_XCC_ID, 0, 4)
	s_waitcnt vmcnt(0)
	s_waitcnt lgkmcnt(0)
	s_barrier
	s_mov_b64 s[2:3], exec
	v_readlane_b32 s6, v254, 1
	v_readlane_b32 s7, v254, 2
	s_and_b64 s[6:7], s[2:3], s[6:7]
	s_mov_b64 exec, s[6:7]
	s_cbranch_execz .LBB0_788
	s_load_dwordx2 s[4:5], s[4:5], 0xd8
	v_mov_b32_e32 v0, 0x23f00
	ds_read_b32 v2, v0
	s_and_b32 s0, s0, 15
	s_lshl_b32 s12, s0, 8
	s_lshl_b32 s14, s0, 2
	v_mov_b32_e32 v3, 1
	v_mov_b32_e32 v1, 0x1000
	s_waitcnt lgkmcnt(0)
	s_add_u32 s6, s4, s12
	s_addc_u32 s7, s5, 0
	global_atomic_add v3, v1, v3, s[6:7] offset:1024 sc0
	buffer_inv sc1
	v_cvt_f32_u32_e32 v4, v2
	v_sub_u32_e32 v0, 0, v2
	v_rcp_iflag_f32_e32 v4, v4
	s_waitcnt vmcnt(1)
	v_mov_b32_e32 v5, v3
	v_mul_f32_e32 v4, 0x4f7ffffe, v4
	v_cvt_u32_f32_e32 v4, v4
	v_mul_lo_u32 v1, v0, v4
	v_mul_hi_u32 v1, v4, v1
	v_add_u32_e32 v1, v4, v1
	v_mul_hi_u32 v1, v5, v1
	v_mul_lo_u32 v3, v1, v2
	v_sub_u32_e32 v3, v5, v3
	v_add_u32_e32 v4, 1, v1
	v_cmp_ge_u32_e32 vcc, v3, v2
	s_nop 1
	v_cndmask_b32_e32 v1, v1, v4, vcc
	v_sub_u32_e32 v4, v3, v2
	v_cndmask_b32_e32 v3, v3, v4, vcc
	v_add_u32_e32 v4, 1, v1
	v_cmp_ge_u32_e32 vcc, v3, v2
	s_nop 1
	v_cndmask_b32_e32 v1, v1, v4, vcc
	v_mul_lo_u32 v4, v2, v1
	v_add_u32_e32 v4, v4, v2
	v_add_u32_e32 v3, 1, v5
	v_readfirstlane_b32 s10, v1
	v_cmp_ne_u32_e32 vcc, v3, v4
	s_cbranch_vccnz .Lgb5_poll
	buffer_wbl2 sc1
	s_add_i32 s11, s10, 1
	v_mov_b32_e32 v0, s14
	v_mov_b32_e32 v1, s11
	v_add_u32_e32 v0, 0x3800, v0
	s_waitcnt vmcnt(0)
	global_store_dword v0, v1, s[4:5] sc1

; DI unsigned xb_ld(unsigned* p)              { return __hip_atomic_load(p, __ATOMIC_RELAXED, __HIP_MEMORY_SCOPE_AGENT); }
; DI unsigned xb_add(unsigned* p, unsigned v) { return __hip_atomic_fetch_add(p, v, __ATOMIC_RELAXED, __HIP_MEMORY_SCOPE_AGENT); }
; #define XB_SPIN(cond, bar) do { unsigned _sp = 0; while (cond) { \
;     if ((++_sp & 255u) == 0u) { if (xb_ld(&(bar)[XB_TMO])) break; if (_sp > XB_SPIN_CAP) { atomicAdd(&(bar)[XB_TMO], 1u); break; } } } } while (0)
; DI void xcd_barrier(const XcdBarrier& b) {
;     asm volatile("s_waitcnt vmcnt(0)" ::: "memory");
;     __syncthreads();
;     if (threadIdx.x == 0) {
;         unsigned* bar = b.bar;
;         __builtin_amdgcn_s_waitcnt(0);
;         unsigned nloc = b.st[0], nx = b.st[1];
;         if (nloc == 0u) { xcd_barrier_complete(bar, b.x, nloc, nx); b.st[0] = nloc; b.st[1] = nx; }
;         const unsigned old = xb_add(&bar[XB_XSUB(b.x)], 1u);
;         const unsigned gen = old / nloc;
;         if (old + 1u == (gen + 1u) * nloc) {
;             __builtin_amdgcn_fence(__ATOMIC_RELEASE, "agent");
;             asm volatile("s_waitcnt vmcnt(0)" ::: "memory");
;             const unsigned og = xb_add(&bar[XB_TOP], 1u);
;             const unsigned tg = og / nx;
;             if (og + 1u == (tg + 1u) * nx) xb_add(&bar[XB_TOPGEN], 1u);
;             else XB_SPIN(xb_ld(&bar[XB_TOPGEN]) == tg, bar);
;             __builtin_amdgcn_fence(__ATOMIC_ACQUIRE, "agent");
;             xb_add(&bar[XB_XGEN(b.x)], 1u);
;             asm volatile("s_waitcnt vmcnt(0)" ::: "memory");
;         } else {
;             XB_SPIN(xb_ld(&bar[XB_XGEN(b.x)]) == gen, bar);
;             __builtin_amdgcn_fence(__ATOMIC_ACQUIRE, "agent");
;             asm volatile("s_waitcnt vmcnt(0)" ::: "memory");
;         }
;     }
;     __syncthreads();
; }
.LBB0_1057:
	v_readlane_b32 s4, v254, 4
	v_readlane_b32 s5, v254, 5
	s_getreg_b32 s0, hwreg(HW_REG_XCC_ID, 0, 4)
	s_waitcnt vmcnt(0)
	s_waitcnt lgkmcnt(0)
	s_barrier
	s_mov_b64 s[2:3], exec
	v_readlane_b32 s6, v254, 1
	v_readlane_b32 s7, v254, 2
	s_and_b64 s[6:7], s[2:3], s[6:7]
	s_mov_b64 exec, s[6:7]
	s_cbranch_execz .LBB0_1109
	s_load_dwordx2 s[4:5], s[4:5], 0xd8
	v_mov_b32_e32 v0, 0x23f00
	ds_read_b32 v2, v0
	s_and_b32 s0, s0, 15
	s_lshl_b32 s12, s0, 8
	s_lshl_b32 s14, s0, 2
	v_mov_b32_e32 v3, 1
	v_mov_b32_e32 v1, 0x1000
	s_waitcnt lgkmcnt(0)
	s_add_u32 s6, s4, s12
	s_addc_u32 s7, s5, 0
	global_atomic_add v3, v1, v3, s[6:7] offset:1024 sc0
	buffer_inv sc1
	v_cvt_f32_u32_e32 v4, v2
	v_sub_u32_e32 v0, 0, v2
	v_rcp_iflag_f32_e32 v4, v4
	s_waitcnt vmcnt(1)
	v_mov_b32_e32 v5, v3
	v_mul_f32_e32 v4, 0x4f7ffffe, v4
	v_cvt_u32_f32_e32 v4, v4
	v_mul_lo_u32 v1, v0, v4
	v_mul_hi_u32 v1, v4, v1
	v_add_u32_e32 v1, v4, v1
	v_mul_hi_u32 v1, v5, v1
	v_mul_lo_u32 v3, v1, v2
	v_sub_u32_e32 v3, v5, v3
	v_add_u32_e32 v4, 1, v1
	v_cmp_ge_u32_e32 vcc, v3, v2
	s_nop 1
	v_cndmask_b32_e32 v1, v1, v4, vcc
	v_sub_u32_e32 v4, v3, v2
	v_cndmask_b32_e32 v3, v3, v4, vcc
	v_add_u32_e32 v4, 1, v1
	v_cmp_ge_u32_e32 vcc, v3, v2
	s_nop 1
	v_cndmask_b32_e32 v1, v1, v4, vcc
	v_mul_lo_u32 v4, v2, v1
	v_add_u32_e32 v4, v4, v2
	v_add_u32_e32 v3, 1, v5
	v_readfirstlane_b32 s10, v1
	v_cmp_ne_u32_e32 vcc, v3, v4
	s_cbranch_vccnz .Lgb6_poll
	buffer_wbl2 sc1
	s_add_i32 s11, s10, 1
	v_mov_b32_e32 v0, s14
	v_mov_b32_e32 v1, s11
	v_add_u32_e32 v0, 0x3800, v0
	s_waitcnt vmcnt(0)
	global_store_dword v0, v1, s[4:5] sc1

; DI unsigned xb_ld(unsigned* p)              { return __hip_atomic_load(p, __ATOMIC_RELAXED, __HIP_MEMORY_SCOPE_AGENT); }
; DI unsigned xb_add(unsigned* p, unsigned v) { return __hip_atomic_fetch_add(p, v, __ATOMIC_RELAXED, __HIP_MEMORY_SCOPE_AGENT); }
; #define XB_SPIN(cond, bar) do { unsigned _sp = 0; while (cond) { \
;     if ((++_sp & 255u) == 0u) { if (xb_ld(&(bar)[XB_TMO])) break; if (_sp > XB_SPIN_CAP) { atomicAdd(&(bar)[XB_TMO], 1u); break; } } } } while (0)
; DI void xcd_barrier(const XcdBarrier& b) {
;     asm volatile("s_waitcnt vmcnt(0)" ::: "memory");
;     __syncthreads();
;     if (threadIdx.x == 0) {
;         unsigned* bar = b.bar;
;         __builtin_amdgcn_s_waitcnt(0);
;         unsigned nloc = b.st[0], nx = b.st[1];
;         if (nloc == 0u) { xcd_barrier_complete(bar, b.x, nloc, nx); b.st[0] = nloc; b.st[1] = nx; }
;         const unsigned old = xb_add(&bar[XB_XSUB(b.x)], 1u);
;         const unsigned gen = old / nloc;
;         if (old + 1u == (gen + 1u) * nloc) {
;             __builtin_amdgcn_fence(__ATOMIC_RELEASE, "agent");
;             asm volatile("s_waitcnt vmcnt(0)" ::: "memory");
;             const unsigned og = xb_add(&bar[XB_TOP], 1u);
;             const unsigned tg = og / nx;
;             if (og + 1u == (tg + 1u) * nx) xb_add(&bar[XB_TOPGEN], 1u);
;             else XB_SPIN(xb_ld(&bar[XB_TOPGEN]) == tg, bar);
;             __builtin_amdgcn_fence(__ATOMIC_ACQUIRE, "agent");
;             xb_add(&bar[XB_XGEN(b.x)], 1u);
;             asm volatile("s_waitcnt vmcnt(0)" ::: "memory");
;         } else {
;             XB_SPIN(xb_ld(&bar[XB_XGEN(b.x)]) == gen, bar);
;             __builtin_amdgcn_fence(__ATOMIC_ACQUIRE, "agent");
;             asm volatile("s_waitcnt vmcnt(0)" ::: "memory");
;         }
;     }
;     __syncthreads();
; }
.LBB0_1478:
	s_load_dwordx2 s[4:5], s[4:5], 0xd8
	v_mov_b32_e32 v0, 0x23f00
	ds_read_b32 v2, v0
	s_and_b32 s0, s0, 15
	s_lshl_b32 s12, s0, 8
	s_lshl_b32 s14, s0, 2
	v_mov_b32_e32 v3, 1
	v_mov_b32_e32 v1, 0x1000
	s_waitcnt lgkmcnt(0)
	s_add_u32 s6, s4, s12
	s_addc_u32 s7, s5, 0
	global_atomic_add v3, v1, v3, s[6:7] offset:1024 sc0
	buffer_inv sc1
	v_cvt_f32_u32_e32 v4, v2
	v_sub_u32_e32 v0, 0, v2
	v_rcp_iflag_f32_e32 v4, v4
	s_waitcnt vmcnt(1)
	v_mov_b32_e32 v5, v3
	v_mul_f32_e32 v4, 0x4f7ffffe, v4
	v_cvt_u32_f32_e32 v4, v4
	v_mul_lo_u32 v1, v0, v4
	v_mul_hi_u32 v1, v4, v1
	v_add_u32_e32 v1, v4, v1
	v_mul_hi_u32 v1, v5, v1
	v_mul_lo_u32 v3, v1, v2
	v_sub_u32_e32 v3, v5, v3
	v_add_u32_e32 v4, 1, v1
	v_cmp_ge_u32_e32 vcc, v3, v2
	s_nop 1
	v_cndmask_b32_e32 v1, v1, v4, vcc
	v_sub_u32_e32 v4, v3, v2
	v_cndmask_b32_e32 v3, v3, v4, vcc
	v_add_u32_e32 v4, 1, v1
	v_cmp_ge_u32_e32 vcc, v3, v2
	s_nop 1
	v_cndmask_b32_e32 v1, v1, v4, vcc
	v_mul_lo_u32 v4, v2, v1
	v_add_u32_e32 v4, v4, v2
	v_add_u32_e32 v3, 1, v5
	v_readfirstlane_b32 s10, v1
	v_cmp_ne_u32_e32 vcc, v3, v4
	s_cbranch_vccnz .Lgb9_poll
	buffer_wbl2 sc1
	s_add_i32 s11, s10, 1
	v_mov_b32_e32 v0, s14
	v_mov_b32_e32 v1, s11
	v_add_u32_e32 v0, 0x3800, v0
	s_waitcnt vmcnt(0)
	global_store_dword v0, v1, s[4:5] sc1

; DI unsigned xb_ld(unsigned* p)              { return __hip_atomic_load(p, __ATOMIC_RELAXED, __HIP_MEMORY_SCOPE_AGENT); }
; #define XB_SPIN(cond, bar) do { unsigned _sp = 0; while (cond) { \
;     if ((++_sp & 255u) == 0u) { if (xb_ld(&(bar)[XB_TMO])) break; if (_sp > XB_SPIN_CAP) { atomicAdd(&(bar)[XB_TMO], 1u); break; } } } } while (0)
; DI void xcd_barrier(const XcdBarrier& b) {
;     ...
;             XB_SPIN(xb_ld(&bar[XB_XGEN(b.x)]) == gen, bar);
;             __builtin_amdgcn_fence(__ATOMIC_ACQUIRE, "agent");
;             asm volatile("s_waitcnt vmcnt(0)" ::: "memory");
;         }
.Lgb9_done:
	s_waitcnt vmcnt(0)
	s_mov_b64 s[8:9], 0
	s_branch .Lgb9_tail
